# comboA + P6 residual loads pipelined 4 groups deep + P5 epilogue loads batched + bias table spread over 6 workgroups + barrier leader releases before its own invalidate
# speedup vs baseline: 1.0518x; 1.0121x over previous
.LBB0_80:
	s_waitcnt vmcnt(30)
	v_pk_mul_f32 v[82:83], v[80:81], v[80:81]
	v_pk_mul_f32 v[84:85], v[78:79], v[78:79]
	s_mul_i32 s0, s81, 24
	v_pk_mov_b32 v[86:87], v[84:85], v[82:83] op_sel:[1,0]
	v_mov_b32_e32 v85, v83
	v_pk_add_f32 v[82:83], v[86:87], v[84:85]
	v_pk_mul_f32 v[84:85], v[76:77], v[76:77]
	v_pk_mul_f32 v[86:87], v[74:75], v[74:75]
	v_pk_add_f32 v[82:83], v[82:83], v[82:83] op_sel:[0,1] op_sel_hi:[1,0]
	v_pk_mov_b32 v[88:89], v[86:87], v[84:85] op_sel:[1,0]
	v_mov_b32_e32 v87, v85
	v_pk_add_f32 v[84:85], v[88:89], v[86:87]
	s_waitcnt vmcnt(29)
	v_mul_f32_e32 v86, v66, v66
	v_mul_f32_e32 v87, v67, v67
	v_pk_add_f32 v[84:85], v[84:85], v[84:85] op_sel:[0,1] op_sel_hi:[1,0]
	v_mov_b32_e32 v83, v86
	v_mov_b32_e32 v85, v87
	v_pk_add_f32 v[82:83], v[82:83], v[84:85]
	s_waitcnt vmcnt(28)
	v_mul_f32_e32 v84, v71, v71
	v_mul_f32_e32 v86, v73, v73
	v_mul_f32_e32 v88, v68, v68
	v_mul_f32_e32 v89, v69, v69
	v_pk_fma_f32 v[84:85], v[70:71], v[70:71], v[84:85] op_sel_hi:[1,1,0]
	v_pk_fma_f32 v[86:87], v[72:73], v[72:73], v[86:87] op_sel_hi:[1,1,0]
	v_mov_b32_e32 v85, v88
	v_mov_b32_e32 v87, v89
	v_pk_add_f32 v[84:85], v[84:85], v[86:87]
	s_add_i32 s1, s0, s70
	v_pk_add_f32 v[82:83], v[82:83], v[84:85]
	s_waitcnt vmcnt(25)
	v_pk_mul_f32 v[84:85], v[62:63], v[62:63]
	v_add_f32_e32 v90, v82, v83
	v_pk_mul_f32 v[82:83], v[64:65], v[64:65]
	s_ashr_i32 s4, s1, 31
	v_pk_mov_b32 v[86:87], v[84:85], v[82:83] op_sel:[1,0]
	v_mov_b32_e32 v85, v83
	v_pk_add_f32 v[82:83], v[86:87], v[84:85]
	v_pk_mul_f32 v[84:85], v[60:61], v[60:61]
	v_pk_mul_f32 v[86:87], v[58:59], v[58:59]
	v_pk_add_f32 v[82:83], v[82:83], v[82:83] op_sel:[0,1] op_sel_hi:[1,0]
	v_pk_mov_b32 v[88:89], v[86:87], v[84:85] op_sel:[1,0]
	v_mov_b32_e32 v87, v85
	v_pk_add_f32 v[84:85], v[88:89], v[86:87]
	s_waitcnt vmcnt(23)
	v_mul_f32_e32 v86, v50, v50
	v_mul_f32_e32 v87, v51, v51
	v_pk_add_f32 v[84:85], v[84:85], v[84:85] op_sel:[0,1] op_sel_hi:[1,0]
	v_mov_b32_e32 v83, v86
	v_mov_b32_e32 v85, v87
	v_pk_add_f32 v[82:83], v[82:83], v[84:85]
	v_mul_f32_e32 v84, v55, v55
	v_mul_f32_e32 v86, v57, v57
	v_mul_f32_e32 v88, v52, v52
	v_mul_f32_e32 v89, v53, v53
	v_pk_fma_f32 v[84:85], v[54:55], v[54:55], v[84:85] op_sel_hi:[1,1,0]
	v_pk_fma_f32 v[86:87], v[56:57], v[56:57], v[86:87] op_sel_hi:[1,1,0]
	v_mov_b32_e32 v85, v88
	v_mov_b32_e32 v87, v89
	v_pk_add_f32 v[84:85], v[84:85], v[86:87]
	s_lshr_b32 s4, s4, 20
	v_pk_add_f32 v[82:83], v[82:83], v[84:85]
	v_pk_mul_f32 v[84:85], v[46:47], v[46:47]
	v_add_f32_e32 v91, v82, v83
	v_pk_mul_f32 v[82:83], v[48:49], v[48:49]
	s_lshl_b32 s0, s1, 2
	v_pk_mov_b32 v[86:87], v[84:85], v[82:83] op_sel:[1,0]
	v_mov_b32_e32 v85, v83
	v_pk_add_f32 v[82:83], v[86:87], v[84:85]
	s_waitcnt vmcnt(22)
	v_pk_mul_f32 v[84:85], v[44:45], v[44:45]
	v_pk_mul_f32 v[86:87], v[42:43], v[42:43]
	v_pk_add_f32 v[82:83], v[82:83], v[82:83] op_sel:[0,1] op_sel_hi:[1,0]
	v_pk_mov_b32 v[88:89], v[86:87], v[84:85] op_sel:[1,0]
	v_mov_b32_e32 v87, v85
	v_pk_add_f32 v[84:85], v[88:89], v[86:87]
	s_waitcnt vmcnt(21)
	v_mul_f32_e32 v86, v34, v34
	v_mul_f32_e32 v87, v35, v35
	v_pk_add_f32 v[84:85], v[84:85], v[84:85] op_sel:[0,1] op_sel_hi:[1,0]
	v_mov_b32_e32 v83, v86
	v_mov_b32_e32 v85, v87
	v_pk_add_f32 v[82:83], v[82:83], v[84:85]
	s_waitcnt vmcnt(20)
	v_mul_f32_e32 v84, v39, v39
	v_mul_f32_e32 v86, v41, v41
	v_mul_f32_e32 v88, v36, v36
	v_mul_f32_e32 v89, v37, v37
	v_pk_fma_f32 v[84:85], v[38:39], v[38:39], v[84:85] op_sel_hi:[1,1,0]
	v_pk_fma_f32 v[86:87], v[40:41], v[40:41], v[86:87] op_sel_hi:[1,1,0]
	v_mov_b32_e32 v85, v88
	v_mov_b32_e32 v87, v89
	v_pk_add_f32 v[84:85], v[84:85], v[86:87]
	s_add_i32 s1, s1, s4
	v_pk_add_f32 v[82:83], v[82:83], v[84:85]
	s_waitcnt vmcnt(19)
	v_pk_mul_f32 v[84:85], v[30:31], v[30:31]
	v_add_f32_e32 v92, v82, v83
	v_pk_mul_f32 v[82:83], v[32:33], v[32:33]
	s_ashr_i32 s4, s1, 12
	v_pk_mov_b32 v[86:87], v[84:85], v[82:83] op_sel:[1,0]
	v_mov_b32_e32 v85, v83
	v_pk_add_f32 v[82:83], v[86:87], v[84:85]
	s_waitcnt vmcnt(17)
	v_pk_mul_f32 v[84:85], v[28:29], v[28:29]
	v_pk_mul_f32 v[86:87], v[26:27], v[26:27]
	v_pk_add_f32 v[82:83], v[82:83], v[82:83] op_sel:[0,1] op_sel_hi:[1,0]
	v_pk_mov_b32 v[88:89], v[86:87], v[84:85] op_sel:[1,0]
	v_mov_b32_e32 v87, v85
	v_pk_add_f32 v[84:85], v[88:89], v[86:87]
	v_mul_f32_e32 v86, v18, v18
	v_mul_f32_e32 v87, v19, v19
	v_pk_add_f32 v[84:85], v[84:85], v[84:85] op_sel:[0,1] op_sel_hi:[1,0]
	v_mov_b32_e32 v83, v86
	v_mov_b32_e32 v85, v87
	v_pk_add_f32 v[82:83], v[82:83], v[84:85]
	s_waitcnt vmcnt(16)
	v_mul_f32_e32 v84, v23, v23
	v_mul_f32_e32 v88, v20, v20
	v_pk_fma_f32 v[84:85], v[22:23], v[22:23], v[84:85] op_sel_hi:[1,1,0]
	v_mul_f32_e32 v86, v25, v25
	v_mov_b32_e32 v85, v88
	ds_bpermute_b32 v88, v1, v90
	v_mul_f32_e32 v89, v21, v21
	v_pk_fma_f32 v[86:87], v[24:25], v[24:25], v[86:87] op_sel_hi:[1,1,0]
	s_ashr_i32 s5, s4, 31
	v_mov_b32_e32 v87, v89
	v_pk_add_f32 v[84:85], v[84:85], v[86:87]
	s_lshl_b64 s[4:5], s[4:5], 24
	v_pk_add_f32 v[82:83], v[82:83], v[84:85]
	ds_bpermute_b32 v84, v1, v91
	v_add_f32_e32 v82, v82, v83
	s_waitcnt lgkmcnt(1)
	v_add_f32_e32 v83, v90, v88
	ds_bpermute_b32 v85, v1, v92
	ds_bpermute_b32 v1, v1, v82
	ds_bpermute_b32 v86, v154, v83
	s_waitcnt lgkmcnt(3)
	v_add_f32_e32 v84, v91, v84
	s_add_u32 s4, s30, s4
	s_waitcnt lgkmcnt(2)
	v_add_f32_e32 v85, v92, v85
	s_waitcnt lgkmcnt(1)
	v_add_f32_e32 v1, v82, v1
	s_waitcnt lgkmcnt(0)
	v_add_f32_e32 v82, v83, v86
	ds_bpermute_b32 v88, v155, v82
	ds_bpermute_b32 v83, v154, v84
	ds_bpermute_b32 v86, v154, v85
	ds_bpermute_b32 v87, v154, v1
	s_addc_u32 s5, s31, s5
	s_waitcnt lgkmcnt(3)
	v_add_f32_e32 v82, v82, v88
	ds_bpermute_b32 v88, v157, v82
	s_waitcnt lgkmcnt(3)
	v_add_f32_e32 v83, v84, v83
	s_waitcnt lgkmcnt(2)
	v_add_f32_e32 v84, v85, v86
	ds_bpermute_b32 v85, v155, v83
	s_ashr_i32 s1, s0, 31
	s_waitcnt lgkmcnt(1)
	v_add_f32_e32 v82, v82, v88
	ds_bpermute_b32 v88, v158, v82
	s_lshl_b64 s[0:1], s[0:1], 10
	s_waitcnt lgkmcnt(1)
	v_add_f32_e32 v83, v83, v85
	ds_bpermute_b32 v85, v157, v83
	ds_bpermute_b32 v86, v155, v84
	s_waitcnt lgkmcnt(2)
	v_add_f32_e32 v82, v82, v88
	ds_bpermute_b32 v88, v156, v82
	s_add_u32 s6, s4, s0
	s_waitcnt lgkmcnt(2)
	v_add_f32_e32 v83, v83, v85
	ds_bpermute_b32 v85, v158, v83
	s_mov_b32 s4, 0xf800000
	s_waitcnt lgkmcnt(1)
	v_add_f32_e32 v82, v82, v88
	v_mov_b32_e32 v88, 0x358637bd
	v_fmamk_f32 v82, v82, 0x3a800000, v88
	v_add_f32_e32 v1, v1, v87
	s_waitcnt lgkmcnt(0)
	v_add_f32_e32 v83, v83, v85
	v_mul_f32_e32 v85, 0x4f800000, v82
	v_cmp_gt_f32_e32 vcc, s4, v82
	ds_bpermute_b32 v87, v155, v1
	v_add_f32_e32 v84, v84, v86
	v_cndmask_b32_e32 v82, v82, v85, vcc
	v_sqrt_f32_e32 v85, v82
	ds_bpermute_b32 v86, v157, v84
	s_waitcnt lgkmcnt(1)
	v_add_f32_e32 v1, v1, v87
	ds_bpermute_b32 v87, v157, v1
	v_add_u32_e32 v90, -1, v85
	v_fma_f32 v91, -v90, v85, v82
	s_addc_u32 s7, s5, s1
	v_cmp_ge_f32_e64 s[0:1], 0, v91
	v_add_u32_e32 v91, 1, v85
	s_waitcnt lgkmcnt(1)
	v_add_f32_e32 v84, v84, v86
	v_cndmask_b32_e64 v90, v85, v90, s[0:1]
	v_fma_f32 v85, -v91, v85, v82
	v_cmp_lt_f32_e64 s[0:1], 0, v85
	ds_bpermute_b32 v86, v158, v84
	s_waitcnt lgkmcnt(1)
	v_add_f32_e32 v1, v1, v87
	v_cndmask_b32_e64 v85, v90, v91, s[0:1]
	v_mul_f32_e32 v90, 0x37800000, v85
	ds_bpermute_b32 v87, v158, v1
	v_cndmask_b32_e32 v85, v85, v90, vcc
	v_mov_b32_e32 v90, 0x260
	v_cmp_class_f32_e32 vcc, v82, v90
	s_waitcnt lgkmcnt(1)
	v_add_f32_e32 v84, v84, v86
	ds_bpermute_b32 v86, v156, v83
	v_cndmask_b32_e32 v82, v85, v82, vcc
	v_div_scale_f32 v85, s[0:1], v82, v82, 1.0
	v_rcp_f32_e32 v91, v85
	s_waitcnt lgkmcnt(1)
	v_add_f32_e32 v1, v1, v87
	ds_bpermute_b32 v87, v156, v84
	s_waitcnt lgkmcnt(1)
	v_add_f32_e32 v92, v83, v86
	v_fma_f32 v83, -v85, v91, 1.0
	v_fmac_f32_e32 v91, v83, v91
	v_div_scale_f32 v83, vcc, 1.0, v82, 1.0
	s_waitcnt lgkmcnt(0)
	v_add_f32_e32 v93, v84, v87
	v_mul_f32_e32 v84, v83, v91
	v_fma_f32 v86, -v85, v84, v83
	v_fmac_f32_e32 v84, v86, v91
	v_fma_f32 v83, -v85, v84, v83
	v_div_fmas_f32 v83, v83, v91, v84
	v_div_fixup_f32 v82, v83, v82, 1.0
	v_pk_mul_f32 v[74:75], v[74:75], v[82:83] op_sel_hi:[1,0]
	v_mov_b32_e32 v147, 0
	v_pk_mul_f32 v[74:75], v[10:11], v[74:75]
	v_pk_mul_f32 v[70:71], v[70:71], v[82:83] op_sel_hi:[1,0]
	v_mov_b32_e32 v87, v147
	v_pk_mul_f32 v[70:71], v[6:7], v[70:71]
	v_cvt_pk_fp8_f32 v87, v74, v75
	v_mov_b32_e32 v74, v147
	v_cvt_pk_fp8_f32 v74, v70, v71
	v_fmamk_f32 v70, v92, 0x3a800000, v88
	v_pk_mul_f32 v[66:67], v[66:67], v[82:83] op_sel_hi:[1,0]
	v_mul_f32_e32 v71, 0x4f800000, v70
	v_cmp_gt_f32_e32 vcc, s4, v70
	v_pk_mul_f32 v[78:79], v[78:79], v[82:83] op_sel_hi:[1,0]
	v_pk_mul_f32 v[80:81], v[80:81], v[82:83] op_sel_hi:[1,0]
	v_pk_mul_f32 v[76:77], v[76:77], v[82:83] op_sel_hi:[1,0]
	v_pk_mul_f32 v[72:73], v[72:73], v[82:83] op_sel_hi:[1,0]
	v_pk_mul_f32 v[68:69], v[68:69], v[82:83] op_sel_hi:[1,0]
	v_pk_mul_f32 v[82:83], v[2:3], v[66:67]
	v_mov_b32_e32 v75, v147
	v_cndmask_b32_e32 v70, v70, v71, vcc
	v_cvt_pk_fp8_f32 v75, v82, v83
	v_sqrt_f32_e32 v71, v70
	v_pk_mul_f32 v[68:69], v[4:5], v[68:69]
	v_lshl_add_u64 v[84:85], s[6:7], 0, v[146:147]
	v_cvt_pk_fp8_f32 v75, v68, v69 op_sel:[0,0,1]
	v_add_u32_e32 v68, -1, v71
	s_mov_b64 s[0:1], 0x1b000000
	v_fma_f32 v69, -v68, v71, v70
	v_lshl_add_u64 v[66:67], v[84:85], 0, s[0:1]
	v_cmp_ge_f32_e64 s[0:1], 0, v69
	v_add_u32_e32 v69, 1, v71
	v_pk_mul_f32 v[78:79], v[14:15], v[78:79]
	v_cndmask_b32_e64 v68, v71, v68, s[0:1]
	v_fma_f32 v71, -v69, v71, v70
	v_cmp_lt_f32_e64 s[0:1], 0, v71
	v_mov_b32_e32 v86, v147
	v_cvt_pk_fp8_f32 v86, v78, v79
	v_cndmask_b32_e64 v68, v68, v69, s[0:1]
	v_mul_f32_e32 v69, 0x37800000, v68
	v_cndmask_b32_e32 v68, v68, v69, vcc
	v_cmp_class_f32_e32 vcc, v70, v90
	v_pk_mul_f32 v[80:81], v[16:17], v[80:81]
	v_pk_mul_f32 v[76:77], v[12:13], v[76:77]
	v_cndmask_b32_e32 v70, v68, v70, vcc
	v_pk_mul_f32 v[72:73], v[8:9], v[72:73]
	v_div_scale_f32 v71, s[0:1], v70, v70, 1.0
	v_cvt_pk_fp8_f32 v86, v80, v81 op_sel:[0,0,1]
	v_cvt_pk_fp8_f32 v87, v76, v77 op_sel:[0,0,1]
	v_cvt_pk_fp8_f32 v74, v72, v73 op_sel:[0,0,1]
	v_rcp_f32_e32 v72, v71
	s_mov_b32 s5, 0x1b000000
	v_add_co_u32_e32 v68, vcc, s5, v84
	ds_bpermute_b32 v89, v156, v1
	s_nop 0
	v_addc_co_u32_e32 v69, vcc, 0, v85, vcc
	global_store_dwordx2 v[68:69], v[86:87], off
	global_store_dwordx2 v[66:67], v[74:75], off offset:512
	v_fma_f32 v68, -v71, v72, 1.0
	v_fmac_f32_e32 v72, v68, v72
	v_div_scale_f32 v68, vcc, 1.0, v70, 1.0
	v_mul_f32_e32 v69, v68, v72
	v_fma_f32 v73, -v71, v69, v68
	v_fmac_f32_e32 v69, v73, v72
	v_fma_f32 v68, -v71, v69, v68
	v_div_fmas_f32 v68, v68, v72, v69
	v_div_fixup_f32 v68, v68, v70, 1.0
	v_pk_mul_f32 v[58:59], v[58:59], v[68:69] op_sel_hi:[1,0]
	v_pk_mul_f32 v[62:63], v[62:63], v[68:69] op_sel_hi:[1,0]
	v_pk_mul_f32 v[64:65], v[64:65], v[68:69] op_sel_hi:[1,0]
	v_pk_mul_f32 v[60:61], v[60:61], v[68:69] op_sel_hi:[1,0]
	v_pk_mul_f32 v[58:59], v[10:11], v[58:59]
	v_pk_mul_f32 v[54:55], v[54:55], v[68:69] op_sel_hi:[1,0]
	v_pk_mul_f32 v[56:57], v[56:57], v[68:69] op_sel_hi:[1,0]
	v_pk_mul_f32 v[50:51], v[50:51], v[68:69] op_sel_hi:[1,0]
	v_pk_mul_f32 v[52:53], v[52:53], v[68:69] op_sel_hi:[1,0]
	v_mov_b32_e32 v69, v147
	v_cvt_pk_fp8_f32 v69, v58, v59
	v_pk_mul_f32 v[60:61], v[12:13], v[60:61]
	v_fmamk_f32 v59, v93, 0x3a800000, v88
	v_cmp_gt_f32_e32 vcc, s4, v59
	v_cvt_pk_fp8_f32 v69, v60, v61 op_sel:[0,0,1]
	v_mul_f32_e32 v60, 0x4f800000, v59
	v_cndmask_b32_e32 v60, v59, v60, vcc
	v_sqrt_f32_e32 v61, v60
	v_pk_mul_f32 v[50:51], v[2:3], v[50:51]
	v_mov_b32_e32 v59, v147
	v_cvt_pk_fp8_f32 v59, v50, v51
	v_add_u32_e32 v50, -1, v61
	v_fma_f32 v51, -v50, v61, v60
	v_pk_mul_f32 v[54:55], v[6:7], v[54:55]
	v_mov_b32_e32 v58, v147
	v_cmp_ge_f32_e64 s[0:1], 0, v51
	v_add_u32_e32 v51, 1, v61
	v_cvt_pk_fp8_f32 v58, v54, v55
	v_fma_f32 v54, -v51, v61, v60
	v_cndmask_b32_e64 v50, v61, v50, s[0:1]
	v_cmp_lt_f32_e64 s[0:1], 0, v54
	v_pk_mul_f32 v[52:53], v[4:5], v[52:53]
	s_waitcnt lgkmcnt(0)
	v_add_f32_e32 v1, v1, v89
	v_cndmask_b32_e64 v50, v50, v51, s[0:1]
	v_mul_f32_e32 v51, 0x37800000, v50
	v_cndmask_b32_e32 v50, v50, v51, vcc
	v_cmp_class_f32_e32 vcc, v60, v90
	v_cvt_pk_fp8_f32 v59, v52, v53 op_sel:[0,0,1]
	v_fmac_f32_e32 v88, 0x3a800000, v1
	v_cndmask_b32_e32 v50, v50, v60, vcc
	v_div_scale_f32 v51, s[0:1], v50, v50, 1.0
	v_rcp_f32_e32 v54, v51
	v_mul_f32_e32 v1, 0x4f800000, v88
	v_pk_mul_f32 v[62:63], v[14:15], v[62:63]
	v_mov_b32_e32 v68, v147
	v_fma_f32 v52, -v51, v54, 1.0
	v_fmac_f32_e32 v54, v52, v54
	v_div_scale_f32 v52, vcc, 1.0, v50, 1.0
	v_mul_f32_e32 v53, v52, v54
	v_fma_f32 v55, -v51, v53, v52
	v_fmac_f32_e32 v53, v55, v54
	v_fma_f32 v51, -v51, v53, v52
	v_div_fmas_f32 v51, v51, v54, v53
	v_div_fixup_f32 v50, v51, v50, 1.0
	v_pk_mul_f32 v[42:43], v[42:43], v[50:51] op_sel_hi:[1,0]
	v_pk_mul_f32 v[34:35], v[34:35], v[50:51] op_sel_hi:[1,0]
	v_pk_mul_f32 v[42:43], v[10:11], v[42:43]
	v_mov_b32_e32 v53, v147
	v_cmp_gt_f32_e32 vcc, s4, v88
	v_pk_mul_f32 v[34:35], v[2:3], v[34:35]
	v_cvt_pk_fp8_f32 v53, v42, v43
	v_mov_b32_e32 v43, v147
	v_cndmask_b32_e32 v1, v88, v1, vcc
	v_cvt_pk_fp8_f32 v43, v34, v35
	v_sqrt_f32_e32 v34, v1
	v_pk_mul_f32 v[36:37], v[36:37], v[50:51] op_sel_hi:[1,0]
	v_pk_mul_f32 v[38:39], v[38:39], v[50:51] op_sel_hi:[1,0]
	v_pk_mul_f32 v[36:37], v[4:5], v[36:37]
	v_add_u32_e32 v35, -1, v34
	v_cvt_pk_fp8_f32 v43, v36, v37 op_sel:[0,0,1]
	v_fma_f32 v36, -v35, v34, v1
	v_cmp_ge_f32_e64 s[0:1], 0, v36
	v_add_u32_e32 v36, 1, v34
	v_pk_mul_f32 v[38:39], v[6:7], v[38:39]
	v_cndmask_b32_e64 v35, v34, v35, s[0:1]
	v_fma_f32 v34, -v36, v34, v1
	v_cmp_lt_f32_e64 s[0:1], 0, v34
	v_mov_b32_e32 v42, v147
	v_cvt_pk_fp8_f32 v42, v38, v39
	v_cndmask_b32_e64 v34, v35, v36, s[0:1]
	v_mul_f32_e32 v35, 0x37800000, v34
	v_cndmask_b32_e32 v34, v34, v35, vcc
	v_cmp_class_f32_e32 vcc, v1, v90
	v_pk_mul_f32 v[46:47], v[46:47], v[50:51] op_sel_hi:[1,0]
	v_cvt_pk_fp8_f32 v68, v62, v63
	v_cndmask_b32_e32 v1, v34, v1, vcc
	v_div_scale_f32 v34, s[0:1], v1, v1, 1.0
	v_rcp_f32_e32 v35, v34
	v_pk_mul_f32 v[46:47], v[14:15], v[46:47]
	v_mov_b32_e32 v52, v147
	v_cvt_pk_fp8_f32 v52, v46, v47
	v_fma_f32 v36, -v34, v35, 1.0
	v_fmac_f32_e32 v35, v36, v35
	v_div_scale_f32 v36, vcc, 1.0, v1, 1.0
	v_mul_f32_e32 v37, v36, v35
	v_fma_f32 v38, -v34, v37, v36
	v_fmac_f32_e32 v37, v38, v35
	v_fma_f32 v34, -v34, v37, v36
	v_div_fmas_f32 v34, v34, v35, v37
	v_div_fixup_f32 v34, v34, v1, 1.0
	v_pk_mul_f32 v[30:31], v[30:31], v[34:35] op_sel_hi:[1,0]
	v_pk_mul_f32 v[22:23], v[22:23], v[34:35] op_sel_hi:[1,0]
	v_pk_mul_f32 v[14:15], v[14:15], v[30:31]
	v_pk_mul_f32 v[26:27], v[26:27], v[34:35] op_sel_hi:[1,0]
	v_pk_mul_f32 v[6:7], v[6:7], v[22:23]
	v_mov_b32_e32 v22, v147
	v_pk_mul_f32 v[10:11], v[10:11], v[26:27]
	v_cvt_pk_fp8_f32 v22, v14, v15
	v_pk_mul_f32 v[14:15], v[18:19], v[34:35] op_sel_hi:[1,0]
	v_mov_b32_e32 v23, v147
	v_pk_mul_f32 v[2:3], v[2:3], v[14:15]
	v_cvt_pk_fp8_f32 v23, v10, v11
	v_mov_b32_e32 v10, v147
	v_mov_b32_e32 v11, v147
	v_cvt_pk_fp8_f32 v10, v6, v7
	v_cvt_pk_fp8_f32 v11, v2, v3
	v_pk_mul_f32 v[48:49], v[48:49], v[50:51] op_sel_hi:[1,0]
	v_pk_mul_f32 v[44:45], v[44:45], v[50:51] op_sel_hi:[1,0]
	v_pk_mul_f32 v[40:41], v[40:41], v[50:51] op_sel_hi:[1,0]
	v_pk_mul_f32 v[32:33], v[32:33], v[34:35] op_sel_hi:[1,0]
	v_pk_mul_f32 v[28:29], v[28:29], v[34:35] op_sel_hi:[1,0]
	v_pk_mul_f32 v[24:25], v[24:25], v[34:35] op_sel_hi:[1,0]
	v_pk_mul_f32 v[18:19], v[20:21], v[34:35] op_sel_hi:[1,0]
	v_pk_mul_f32 v[64:65], v[16:17], v[64:65]
	v_pk_mul_f32 v[56:57], v[8:9], v[56:57]
	v_pk_mul_f32 v[48:49], v[16:17], v[48:49]
	v_pk_mul_f32 v[44:45], v[12:13], v[44:45]
	v_pk_mul_f32 v[40:41], v[8:9], v[40:41]
	v_pk_mul_f32 v[16:17], v[16:17], v[32:33]
	v_pk_mul_f32 v[12:13], v[12:13], v[28:29]
	v_pk_mul_f32 v[8:9], v[8:9], v[24:25]
	v_pk_mul_f32 v[2:3], v[4:5], v[18:19]
	v_cvt_pk_fp8_f32 v68, v64, v65 op_sel:[0,0,1]
	v_cvt_pk_fp8_f32 v58, v56, v57 op_sel:[0,0,1]
	v_cvt_pk_fp8_f32 v22, v16, v17 op_sel:[0,0,1]
	v_cvt_pk_fp8_f32 v23, v12, v13 op_sel:[0,0,1]
	v_cvt_pk_fp8_f32 v10, v8, v9 op_sel:[0,0,1]
	v_cvt_pk_fp8_f32 v11, v2, v3 op_sel:[0,0,1]
	v_cvt_pk_fp8_f32 v52, v48, v49 op_sel:[0,0,1]
	v_cvt_pk_fp8_f32 v53, v44, v45 op_sel:[0,0,1]
	v_cvt_pk_fp8_f32 v42, v40, v41 op_sel:[0,0,1]
	s_add_i32 s81, s81, -1
	s_sub_i32 s0, s81, s82
	s_cmp_lt_u32 s0, 6
	global_store_dwordx2 v[66:67], v[68:69], off offset:1024
	global_store_dwordx2 v[66:67], v[58:59], off offset:1536
	global_store_dwordx2 v[66:67], v[52:53], off offset:2048
	global_store_dwordx2 v[66:67], v[42:43], off offset:2560
	global_store_dwordx2 v[66:67], v[22:23], off offset:3072
	global_store_dwordx2 v[66:67], v[10:11], off offset:3584
	s_cbranch_scc0 .LBB0_109
	s_lshl_b32 s4, s0, 9
	s_lshl_b32 s5, s0, 13
	v_lshlrev_b32_e32 v146, 4, v0
	v_lshl_add_u64 v[2:3], s[30:31], 0, v[146:147]
	s_mov_b64 s[0:1], 0x1f200000
	v_lshl_add_u64 v[6:7], v[2:3], 0, s[0:1]
	v_add_u32_e32 v8, s4, v0
	v_mov_b32_e32 v146, s5
	v_lshl_add_u64 v[6:7], v[6:7], 0, v[146:147]
	v_sub_u32_e32 v1, 0, v8
	s_mov_b64 s[4:5], 0
	s_mov_b32 s14, 0xaaaaaaab
	s_movk_i32 s15, 0x180
	s_movk_i32 s16, 0xfe80
	s_movk_i32 s17, 0xbf
	s_movk_i32 s24, 0x81
	s_movk_i32 s25, 0x17f
	s_movk_i32 s26, 0x80
	s_movk_i32 s27, 0xbe
	s_movk_i32 s33, 0x17e
	s_movk_i32 s36, 0xbd
	s_movk_i32 s37, 0x17d
	s_movk_i32 s38, 0xbc
	s_movk_i32 s39, 0x17c
	s_mov_b64 s[6:7], 0x2000
	s_movk_i32 s40, 0x9ff
	s_branch .LBB0_84

.LBB0_83:
	s_or_b64 exec, exec, s[0:1]
	global_store_dwordx4 v[6:7], v[2:5], off
	s_mov_b64 vcc, exec
	v_lshl_add_u64 v[6:7], v[6:7], 0, s[6:7]
	v_add_u32_e32 v2, 0x200, v8
	v_add_u32_e32 v1, 0xfffffe00, v1
	s_or_b64 s[4:5], vcc, s[4:5]
	v_mov_b32_e32 v8, v2
	s_andn2_b64 exec, exec, s[4:5]
	s_cbranch_execz .LBB0_108

.LBB0_157:
	s_or_b64 exec, exec, s[4:5]
	v_mov_b32_e32 v1, 0
	v_mov_b32_e32 v2, 1
	s_waitcnt vmcnt(0)
	global_atomic_add v1, v2, s[6:7]
	buffer_inv sc1
	s_waitcnt vmcnt(0)

.LBB0_493:
	s_or_b64 exec, exec, s[4:5]
	v_mov_b32_e32 v1, 0x2000
	v_mov_b32_e32 v2, 1
	s_waitcnt vmcnt(0)
	global_atomic_add v1, v2, s[2:3] offset:1024
	buffer_inv sc1
	s_waitcnt vmcnt(0)

.LBB0_641:
	s_or_b64 exec, exec, s[4:5]
	v_mov_b32_e32 v1, 0x2000
	v_mov_b32_e32 v2, 1
	s_waitcnt vmcnt(0)
	global_atomic_add v1, v2, s[0:1] offset:1024
	buffer_inv sc1
	s_waitcnt vmcnt(0)

.LBB0_742:
	v_ashrrev_i32_e32 v193, 31, v192
	v_mov_b32_e32 v135, s65
	v_or_b32_e32 v134, s64, v182
	v_lshlrev_b64 v[4:5], 10, v[192:193]
	v_lshl_add_u64 v[4:5], v[134:135], 0, v[4:5]
	v_lshlrev_b64 v[4:5], 1, v[4:5]
	v_lshl_add_u64 v[234:235], s[6:7], 0, v[4:5]
	v_lshl_add_u64 v[236:237], s[8:9], 0, v[4:5]
	v_mov_b32_e32 v238, 0x8000
	v_mov_b32_e32 v239, 0
	v_mov_b32_e32 v240, 0x28000
	v_mov_b32_e32 v241, 0
	s_andn2_b64 vcc, exec, s[54:55]
	s_mov_b64 s[54:55], -1
	global_load_dwordx4 v[134:137], v[234:235], off
	global_load_dwordx4 v[138:141], v[234:235], off offset:256
	v_lshl_add_u64 v[234:235], v[234:235], 0, v[238:239]
	global_load_dwordx4 v[142:145], v[234:235], off
	global_load_dwordx4 v[146:149], v[234:235], off offset:256
	v_lshl_add_u64 v[234:235], v[234:235], 0, v[238:239]
	global_load_dwordx4 v[150:153], v[234:235], off
	global_load_dwordx4 v[154:157], v[234:235], off offset:256
	v_lshl_add_u64 v[234:235], v[234:235], 0, v[238:239]
	global_load_dwordx4 v[158:161], v[234:235], off
	global_load_dwordx4 v[162:165], v[234:235], off offset:256
	v_lshl_add_u64 v[234:235], v[234:235], 0, v[240:241]
	global_load_dwordx4 v[166:169], v[234:235], off
	global_load_dwordx4 v[170:173], v[234:235], off offset:256
	v_lshl_add_u64 v[234:235], v[234:235], 0, v[238:239]
	global_load_dwordx4 v[202:205], v[234:235], off
	global_load_dwordx4 v[206:209], v[234:235], off offset:256
	v_lshl_add_u64 v[234:235], v[234:235], 0, v[238:239]
	global_load_dwordx4 v[210:213], v[234:235], off
	global_load_dwordx4 v[214:217], v[234:235], off offset:256
	v_lshl_add_u64 v[234:235], v[234:235], 0, v[238:239]
	global_load_dwordx4 v[218:221], v[234:235], off
	global_load_dwordx4 v[222:225], v[234:235], off offset:256
	s_waitcnt vmcnt(15)
	v_lshlrev_b32_e32 v242, 16, v134
	v_and_b32_e32 v243, 0xffff0000, v134
	v_lshlrev_b32_e32 v244, 16, v135
	v_and_b32_e32 v245, 0xffff0000, v135
	v_lshlrev_b32_e32 v246, 16, v136
	v_and_b32_e32 v247, 0xffff0000, v136
	v_lshlrev_b32_e32 v248, 16, v137
	v_and_b32_e32 v249, 0xffff0000, v137
	v_mul_f32_e32 v242, v130, v242
	v_mul_f32_e32 v243, v131, v243
	v_mul_f32_e32 v244, v132, v244
	v_mul_f32_e32 v245, v133, v245
	v_mul_f32_e32 v246, v126, v246
	v_mul_f32_e32 v247, v127, v247
	v_mul_f32_e32 v248, v128, v248
	v_mul_f32_e32 v249, v129, v249
	v_cvt_pk_bf16_f32 v134, v242, v243
	v_cvt_pk_bf16_f32 v135, v244, v245
	v_cvt_pk_bf16_f32 v136, v246, v247
	v_cvt_pk_bf16_f32 v137, v248, v249
	global_store_dwordx4 v[236:237], v[134:137], off
	s_waitcnt vmcnt(15)
	v_lshlrev_b32_e32 v242, 16, v138
	v_and_b32_e32 v243, 0xffff0000, v138
	v_lshlrev_b32_e32 v244, 16, v139
	v_and_b32_e32 v245, 0xffff0000, v139
	v_lshlrev_b32_e32 v246, 16, v140
	v_and_b32_e32 v247, 0xffff0000, v140
	v_lshlrev_b32_e32 v248, 16, v141
	v_and_b32_e32 v249, 0xffff0000, v141
	v_mul_f32_e32 v242, v122, v242
	v_mul_f32_e32 v243, v123, v243
	v_mul_f32_e32 v244, v124, v244
	v_mul_f32_e32 v245, v125, v245
	v_mul_f32_e32 v246, v118, v246
	v_mul_f32_e32 v247, v119, v247
	v_mul_f32_e32 v248, v120, v248
	v_mul_f32_e32 v249, v121, v249
	v_cvt_pk_bf16_f32 v138, v242, v243
	v_cvt_pk_bf16_f32 v139, v244, v245
	v_cvt_pk_bf16_f32 v140, v246, v247
	v_cvt_pk_bf16_f32 v141, v248, v249
	global_store_dwordx4 v[236:237], v[138:141], off offset:256
	v_lshl_add_u64 v[236:237], v[236:237], 0, v[238:239]
	s_waitcnt vmcnt(15)
	v_lshlrev_b32_e32 v242, 16, v142
	v_and_b32_e32 v243, 0xffff0000, v142
	v_lshlrev_b32_e32 v244, 16, v143
	v_and_b32_e32 v245, 0xffff0000, v143
	v_lshlrev_b32_e32 v246, 16, v144
	v_and_b32_e32 v247, 0xffff0000, v144
	v_lshlrev_b32_e32 v248, 16, v145
	v_and_b32_e32 v249, 0xffff0000, v145
	v_mul_f32_e32 v242, v114, v242
	v_mul_f32_e32 v243, v115, v243
	v_mul_f32_e32 v244, v116, v244
	v_mul_f32_e32 v245, v117, v245
	v_mul_f32_e32 v246, v110, v246
	v_mul_f32_e32 v247, v111, v247
	v_mul_f32_e32 v248, v112, v248
	v_mul_f32_e32 v249, v113, v249
	v_cvt_pk_bf16_f32 v142, v242, v243
	v_cvt_pk_bf16_f32 v143, v244, v245
	v_cvt_pk_bf16_f32 v144, v246, v247
	v_cvt_pk_bf16_f32 v145, v248, v249
	global_store_dwordx4 v[236:237], v[142:145], off
	s_waitcnt vmcnt(15)
	v_lshlrev_b32_e32 v242, 16, v146
	v_and_b32_e32 v243, 0xffff0000, v146
	v_lshlrev_b32_e32 v244, 16, v147
	v_and_b32_e32 v245, 0xffff0000, v147
	v_lshlrev_b32_e32 v246, 16, v148
	v_and_b32_e32 v247, 0xffff0000, v148
	v_lshlrev_b32_e32 v248, 16, v149
	v_and_b32_e32 v249, 0xffff0000, v149
	v_mul_f32_e32 v242, v106, v242
	v_mul_f32_e32 v243, v107, v243
	v_mul_f32_e32 v244, v108, v244
	v_mul_f32_e32 v245, v109, v245
	v_mul_f32_e32 v246, v102, v246
	v_mul_f32_e32 v247, v103, v247
	v_mul_f32_e32 v248, v104, v248
	v_mul_f32_e32 v249, v105, v249
	v_cvt_pk_bf16_f32 v146, v242, v243
	v_cvt_pk_bf16_f32 v147, v244, v245
	v_cvt_pk_bf16_f32 v148, v246, v247
	v_cvt_pk_bf16_f32 v149, v248, v249
	global_store_dwordx4 v[236:237], v[146:149], off offset:256
	v_lshl_add_u64 v[236:237], v[236:237], 0, v[238:239]
	s_waitcnt vmcnt(15)
	v_lshlrev_b32_e32 v242, 16, v150
	v_and_b32_e32 v243, 0xffff0000, v150
	v_lshlrev_b32_e32 v244, 16, v151
	v_and_b32_e32 v245, 0xffff0000, v151
	v_lshlrev_b32_e32 v246, 16, v152
	v_and_b32_e32 v247, 0xffff0000, v152
	v_lshlrev_b32_e32 v248, 16, v153
	v_and_b32_e32 v249, 0xffff0000, v153
	v_mul_f32_e32 v242, v98, v242
	v_mul_f32_e32 v243, v99, v243
	v_mul_f32_e32 v244, v100, v244
	v_mul_f32_e32 v245, v101, v245
	v_mul_f32_e32 v246, v94, v246
	v_mul_f32_e32 v247, v95, v247
	v_mul_f32_e32 v248, v96, v248
	v_mul_f32_e32 v249, v97, v249
	v_cvt_pk_bf16_f32 v150, v242, v243
	v_cvt_pk_bf16_f32 v151, v244, v245
	v_cvt_pk_bf16_f32 v152, v246, v247
	v_cvt_pk_bf16_f32 v153, v248, v249
	global_store_dwordx4 v[236:237], v[150:153], off
	s_waitcnt vmcnt(15)
	v_lshlrev_b32_e32 v242, 16, v154
	v_and_b32_e32 v243, 0xffff0000, v154
	v_lshlrev_b32_e32 v244, 16, v155
	v_and_b32_e32 v245, 0xffff0000, v155
	v_lshlrev_b32_e32 v246, 16, v156
	v_and_b32_e32 v247, 0xffff0000, v156
	v_lshlrev_b32_e32 v248, 16, v157
	v_and_b32_e32 v249, 0xffff0000, v157
	v_mul_f32_e32 v242, v90, v242
	v_mul_f32_e32 v243, v91, v243
	v_mul_f32_e32 v244, v92, v244
	v_mul_f32_e32 v245, v93, v245
	v_mul_f32_e32 v246, v86, v246
	v_mul_f32_e32 v247, v87, v247
	v_mul_f32_e32 v248, v88, v248
	v_mul_f32_e32 v249, v89, v249
	v_cvt_pk_bf16_f32 v154, v242, v243
	v_cvt_pk_bf16_f32 v155, v244, v245
	v_cvt_pk_bf16_f32 v156, v246, v247
	v_cvt_pk_bf16_f32 v157, v248, v249
	global_store_dwordx4 v[236:237], v[154:157], off offset:256
	v_lshl_add_u64 v[236:237], v[236:237], 0, v[238:239]
	s_waitcnt vmcnt(15)
	v_lshlrev_b32_e32 v242, 16, v158
	v_and_b32_e32 v243, 0xffff0000, v158
	v_lshlrev_b32_e32 v244, 16, v159
	v_and_b32_e32 v245, 0xffff0000, v159
	v_lshlrev_b32_e32 v246, 16, v160
	v_and_b32_e32 v247, 0xffff0000, v160
	v_lshlrev_b32_e32 v248, 16, v161
	v_and_b32_e32 v249, 0xffff0000, v161
	v_mul_f32_e32 v242, v82, v242
	v_mul_f32_e32 v243, v83, v243
	v_mul_f32_e32 v244, v84, v244
	v_mul_f32_e32 v245, v85, v245
	v_mul_f32_e32 v246, v78, v246
	v_mul_f32_e32 v247, v79, v247
	v_mul_f32_e32 v248, v80, v248
	v_mul_f32_e32 v249, v81, v249
	v_cvt_pk_bf16_f32 v158, v242, v243
	v_cvt_pk_bf16_f32 v159, v244, v245
	v_cvt_pk_bf16_f32 v160, v246, v247
	v_cvt_pk_bf16_f32 v161, v248, v249
	global_store_dwordx4 v[236:237], v[158:161], off
	s_waitcnt vmcnt(15)
	v_lshlrev_b32_e32 v242, 16, v162
	v_and_b32_e32 v243, 0xffff0000, v162
	v_lshlrev_b32_e32 v244, 16, v163
	v_and_b32_e32 v245, 0xffff0000, v163
	v_lshlrev_b32_e32 v246, 16, v164
	v_and_b32_e32 v247, 0xffff0000, v164
	v_lshlrev_b32_e32 v248, 16, v165
	v_and_b32_e32 v249, 0xffff0000, v165
	v_mul_f32_e32 v242, v74, v242
	v_mul_f32_e32 v243, v75, v243
	v_mul_f32_e32 v244, v76, v244
	v_mul_f32_e32 v245, v77, v245
	v_mul_f32_e32 v246, v70, v246
	v_mul_f32_e32 v247, v71, v247
	v_mul_f32_e32 v248, v72, v248
	v_mul_f32_e32 v249, v73, v249
	v_cvt_pk_bf16_f32 v162, v242, v243
	v_cvt_pk_bf16_f32 v163, v244, v245
	v_cvt_pk_bf16_f32 v164, v246, v247
	v_cvt_pk_bf16_f32 v165, v248, v249
	global_store_dwordx4 v[236:237], v[162:165], off offset:256
	v_lshl_add_u64 v[236:237], v[236:237], 0, v[240:241]
	s_waitcnt vmcnt(15)
	v_lshlrev_b32_e32 v242, 16, v166
	v_and_b32_e32 v243, 0xffff0000, v166
	v_lshlrev_b32_e32 v244, 16, v167
	v_and_b32_e32 v245, 0xffff0000, v167
	v_lshlrev_b32_e32 v246, 16, v168
	v_and_b32_e32 v247, 0xffff0000, v168
	v_lshlrev_b32_e32 v248, 16, v169
	v_and_b32_e32 v249, 0xffff0000, v169
	v_mul_f32_e32 v242, v66, v242
	v_mul_f32_e32 v243, v67, v243
	v_mul_f32_e32 v244, v68, v244
	v_mul_f32_e32 v245, v69, v245
	v_mul_f32_e32 v246, v62, v246
	v_mul_f32_e32 v247, v63, v247
	v_mul_f32_e32 v248, v64, v248
	v_mul_f32_e32 v249, v65, v249
	v_cvt_pk_bf16_f32 v166, v242, v243
	v_cvt_pk_bf16_f32 v167, v244, v245
	v_cvt_pk_bf16_f32 v168, v246, v247
	v_cvt_pk_bf16_f32 v169, v248, v249
	global_store_dwordx4 v[236:237], v[166:169], off
	s_waitcnt vmcnt(15)
	v_lshlrev_b32_e32 v242, 16, v170
	v_and_b32_e32 v243, 0xffff0000, v170
	v_lshlrev_b32_e32 v244, 16, v171
	v_and_b32_e32 v245, 0xffff0000, v171
	v_lshlrev_b32_e32 v246, 16, v172
	v_and_b32_e32 v247, 0xffff0000, v172
	v_lshlrev_b32_e32 v248, 16, v173
	v_and_b32_e32 v249, 0xffff0000, v173
	v_mul_f32_e32 v242, v58, v242
	v_mul_f32_e32 v243, v59, v243
	v_mul_f32_e32 v244, v60, v244
	v_mul_f32_e32 v245, v61, v245
	v_mul_f32_e32 v246, v54, v246
	v_mul_f32_e32 v247, v55, v247
	v_mul_f32_e32 v248, v56, v248
	v_mul_f32_e32 v249, v57, v249
	v_cvt_pk_bf16_f32 v170, v242, v243
	v_cvt_pk_bf16_f32 v171, v244, v245
	v_cvt_pk_bf16_f32 v172, v246, v247
	v_cvt_pk_bf16_f32 v173, v248, v249
	global_store_dwordx4 v[236:237], v[170:173], off offset:256
	v_lshl_add_u64 v[236:237], v[236:237], 0, v[238:239]
	s_waitcnt vmcnt(15)
	v_lshlrev_b32_e32 v242, 16, v202
	v_and_b32_e32 v243, 0xffff0000, v202
	v_lshlrev_b32_e32 v244, 16, v203
	v_and_b32_e32 v245, 0xffff0000, v203
	v_lshlrev_b32_e32 v246, 16, v204
	v_and_b32_e32 v247, 0xffff0000, v204
	v_lshlrev_b32_e32 v248, 16, v205
	v_and_b32_e32 v249, 0xffff0000, v205
	v_mul_f32_e32 v242, v50, v242
	v_mul_f32_e32 v243, v51, v243
	v_mul_f32_e32 v244, v52, v244
	v_mul_f32_e32 v245, v53, v245
	v_mul_f32_e32 v246, v46, v246
	v_mul_f32_e32 v247, v47, v247
	v_mul_f32_e32 v248, v48, v248
	v_mul_f32_e32 v249, v49, v249
	v_cvt_pk_bf16_f32 v202, v242, v243
	v_cvt_pk_bf16_f32 v203, v244, v245
	v_cvt_pk_bf16_f32 v204, v246, v247
	v_cvt_pk_bf16_f32 v205, v248, v249
	global_store_dwordx4 v[236:237], v[202:205], off
	s_waitcnt vmcnt(15)
	v_lshlrev_b32_e32 v242, 16, v206
	v_and_b32_e32 v243, 0xffff0000, v206
	v_lshlrev_b32_e32 v244, 16, v207
	v_and_b32_e32 v245, 0xffff0000, v207
	v_lshlrev_b32_e32 v246, 16, v208
	v_and_b32_e32 v247, 0xffff0000, v208
	v_lshlrev_b32_e32 v248, 16, v209
	v_and_b32_e32 v249, 0xffff0000, v209
	v_mul_f32_e32 v242, v42, v242
	v_mul_f32_e32 v243, v43, v243
	v_mul_f32_e32 v244, v44, v244
	v_mul_f32_e32 v245, v45, v245
	v_mul_f32_e32 v246, v38, v246
	v_mul_f32_e32 v247, v39, v247
	v_mul_f32_e32 v248, v40, v248
	v_mul_f32_e32 v249, v41, v249
	v_cvt_pk_bf16_f32 v206, v242, v243
	v_cvt_pk_bf16_f32 v207, v244, v245
	v_cvt_pk_bf16_f32 v208, v246, v247
	v_cvt_pk_bf16_f32 v209, v248, v249
	global_store_dwordx4 v[236:237], v[206:209], off offset:256
	v_lshl_add_u64 v[236:237], v[236:237], 0, v[238:239]
	s_waitcnt vmcnt(15)
	v_lshlrev_b32_e32 v242, 16, v210
	v_and_b32_e32 v243, 0xffff0000, v210
	v_lshlrev_b32_e32 v244, 16, v211
	v_and_b32_e32 v245, 0xffff0000, v211
	v_lshlrev_b32_e32 v246, 16, v212
	v_and_b32_e32 v247, 0xffff0000, v212
	v_lshlrev_b32_e32 v248, 16, v213
	v_and_b32_e32 v249, 0xffff0000, v213
	v_mul_f32_e32 v242, v34, v242
	v_mul_f32_e32 v243, v35, v243
	v_mul_f32_e32 v244, v36, v244
	v_mul_f32_e32 v245, v37, v245
	v_mul_f32_e32 v246, v30, v246
	v_mul_f32_e32 v247, v31, v247
	v_mul_f32_e32 v248, v32, v248
	v_mul_f32_e32 v249, v33, v249
	v_cvt_pk_bf16_f32 v210, v242, v243
	v_cvt_pk_bf16_f32 v211, v244, v245
	v_cvt_pk_bf16_f32 v212, v246, v247
	v_cvt_pk_bf16_f32 v213, v248, v249
	global_store_dwordx4 v[236:237], v[210:213], off
	s_waitcnt vmcnt(15)
	v_lshlrev_b32_e32 v242, 16, v214
	v_and_b32_e32 v243, 0xffff0000, v214
	v_lshlrev_b32_e32 v244, 16, v215
	v_and_b32_e32 v245, 0xffff0000, v215
	v_lshlrev_b32_e32 v246, 16, v216
	v_and_b32_e32 v247, 0xffff0000, v216
	v_lshlrev_b32_e32 v248, 16, v217
	v_and_b32_e32 v249, 0xffff0000, v217
	v_mul_f32_e32 v242, v26, v242
	v_mul_f32_e32 v243, v27, v243
	v_mul_f32_e32 v244, v28, v244
	v_mul_f32_e32 v245, v29, v245
	v_mul_f32_e32 v246, v22, v246
	v_mul_f32_e32 v247, v23, v247
	v_mul_f32_e32 v248, v24, v248
	v_mul_f32_e32 v249, v25, v249
	v_cvt_pk_bf16_f32 v214, v242, v243
	v_cvt_pk_bf16_f32 v215, v244, v245
	v_cvt_pk_bf16_f32 v216, v246, v247
	v_cvt_pk_bf16_f32 v217, v248, v249
	global_store_dwordx4 v[236:237], v[214:217], off offset:256
	v_lshl_add_u64 v[236:237], v[236:237], 0, v[238:239]
	s_waitcnt vmcnt(15)
	v_lshlrev_b32_e32 v242, 16, v218
	v_and_b32_e32 v243, 0xffff0000, v218
	v_lshlrev_b32_e32 v244, 16, v219
	v_and_b32_e32 v245, 0xffff0000, v219
	v_lshlrev_b32_e32 v246, 16, v220
	v_and_b32_e32 v247, 0xffff0000, v220
	v_lshlrev_b32_e32 v248, 16, v221
	v_and_b32_e32 v249, 0xffff0000, v221
	v_mul_f32_e32 v242, v18, v242
	v_mul_f32_e32 v243, v19, v243
	v_mul_f32_e32 v244, v20, v244
	v_mul_f32_e32 v245, v21, v245
	v_mul_f32_e32 v246, v14, v246
	v_mul_f32_e32 v247, v15, v247
	v_mul_f32_e32 v248, v16, v248
	v_mul_f32_e32 v249, v17, v249
	v_cvt_pk_bf16_f32 v218, v242, v243
	v_cvt_pk_bf16_f32 v219, v244, v245
	v_cvt_pk_bf16_f32 v220, v246, v247
	v_cvt_pk_bf16_f32 v221, v248, v249
	global_store_dwordx4 v[236:237], v[218:221], off
	s_waitcnt vmcnt(15)
	v_lshlrev_b32_e32 v242, 16, v222
	v_and_b32_e32 v243, 0xffff0000, v222
	v_lshlrev_b32_e32 v244, 16, v223
	v_and_b32_e32 v245, 0xffff0000, v223
	v_lshlrev_b32_e32 v246, 16, v224
	v_and_b32_e32 v247, 0xffff0000, v224
	v_lshlrev_b32_e32 v248, 16, v225
	v_and_b32_e32 v249, 0xffff0000, v225
	v_mul_f32_e32 v242, v10, v242
	v_mul_f32_e32 v243, v11, v243
	v_mul_f32_e32 v244, v12, v244
	v_mul_f32_e32 v245, v13, v245
	v_mul_f32_e32 v246, v6, v246
	v_mul_f32_e32 v247, v7, v247
	v_mul_f32_e32 v248, v8, v248
	v_mul_f32_e32 v249, v9, v249
	v_cvt_pk_bf16_f32 v222, v242, v243
	v_cvt_pk_bf16_f32 v223, v244, v245
	v_cvt_pk_bf16_f32 v224, v246, v247
	v_cvt_pk_bf16_f32 v225, v248, v249
	global_store_dwordx4 v[236:237], v[222:225], off offset:256
	s_cbranch_vccnz .LBB0_727
	s_andn2_b64 vcc, exec, s[2:3]
	s_cbranch_vccnz .LBB0_726
	s_barrier
	s_branch .LBB0_726

.LBB0_806:
	s_sext_i32_i8 s0, s0
	s_lshl_b32 s4, s1, 5
	s_lshl_b32 s0, s0, 8
	s_or_b32 s0, s0, s4
	v_lshrrev_b32_e32 v130, 2, v136
	s_lshl_b32 s41, s16, 8
	v_and_or_b32 v132, v130, 12, s0
	s_add_i32 s0, s41, s44
	v_or_b32_e32 v130, s0, v137
	v_ashrrev_i32_e32 v131, 31, v130
	v_ashrrev_i32_e32 v133, 31, v132
	v_lshlrev_b64 v[134:135], 12, v[130:131]
	v_lshl_add_u64 v[134:135], s[12:13], 0, v[134:135]
	v_lshlrev_b64 v[152:153], 2, v[132:133]
	v_lshl_add_u64 v[160:161], v[134:135], 0, v[152:153]
	s_barrier
	v_mov_b32_e32 v242, 0x10000
	v_mov_b32_e32 v243, 0
	v_mov_b32_e32 v244, 0x50000
	v_mov_b32_e32 v245, 0
	v_lshl_add_u64 v[228:229], v[160:161], 0, v[242:243]
	v_lshl_add_u64 v[230:231], v[228:229], 0, v[242:243]
	v_lshl_add_u64 v[232:233], v[230:231], 0, v[242:243]
	v_lshl_add_u64 v[234:235], v[232:233], 0, v[244:245]
	v_lshl_add_u64 v[236:237], v[234:235], 0, v[242:243]
	v_lshl_add_u64 v[238:239], v[236:237], 0, v[242:243]
	v_lshl_add_u64 v[240:241], v[238:239], 0, v[242:243]
	global_load_dwordx4 v[132:135], v[160:161], off
	global_load_dwordx4 v[138:141], v[160:161], off offset:64
	global_load_dwordx4 v[142:145], v[160:161], off offset:512
	s_nop 0
	global_load_dwordx4 v[160:163], v[160:161], off offset:576
	global_load_dwordx4 v[176:179], v[228:229], off
	global_load_dwordx4 v[180:183], v[228:229], off offset:64
	global_load_dwordx4 v[184:187], v[228:229], off offset:512
	global_load_dwordx4 v[188:191], v[228:229], off offset:576
	global_load_dwordx4 v[192:195], v[230:231], off
	global_load_dwordx4 v[196:199], v[230:231], off offset:64
	global_load_dwordx4 v[200:203], v[230:231], off offset:512
	global_load_dwordx4 v[204:207], v[230:231], off offset:576
	global_load_dwordx4 v[208:211], v[232:233], off
	global_load_dwordx4 v[212:215], v[232:233], off offset:64
	global_load_dwordx4 v[216:219], v[232:233], off offset:512
	global_load_dwordx4 v[224:227], v[232:233], off offset:576
	s_waitcnt vmcnt(12)
	v_pk_add_f32 v[84:85], v[84:85], v[134:135]
	v_pk_add_f32 v[82:83], v[82:83], v[132:133]
	v_pk_add_f32 v[88:89], v[88:89], v[140:141]
	v_pk_add_f32 v[86:87], v[86:87], v[138:139]
	v_pk_add_f32 v[92:93], v[92:93], v[144:145]
	v_pk_add_f32 v[90:91], v[90:91], v[142:143]
	v_pk_add_f32 v[96:97], v[96:97], v[162:163]
	v_pk_add_f32 v[94:95], v[94:95], v[160:161]
	global_load_dwordx4 v[132:135], v[234:235], off
	global_load_dwordx4 v[138:141], v[234:235], off offset:64
	global_load_dwordx4 v[142:145], v[234:235], off offset:512
	global_load_dwordx4 v[160:163], v[234:235], off offset:576
	s_waitcnt vmcnt(12)
	v_pk_add_f32 v[128:129], v[128:129], v[178:179]
	v_pk_add_f32 v[126:127], v[126:127], v[176:177]
	v_pk_add_f32 v[124:125], v[124:125], v[182:183]
	v_pk_add_f32 v[122:123], v[122:123], v[180:181]
	v_pk_add_f32 v[120:121], v[120:121], v[186:187]
	v_pk_add_f32 v[118:119], v[118:119], v[184:185]
	v_pk_add_f32 v[60:61], v[60:61], v[190:191]
	v_pk_add_f32 v[58:59], v[58:59], v[188:189]
	global_load_dwordx4 v[176:179], v[236:237], off
	global_load_dwordx4 v[180:183], v[236:237], off offset:64
	global_load_dwordx4 v[184:187], v[236:237], off offset:512
	global_load_dwordx4 v[188:191], v[236:237], off offset:576
	s_waitcnt vmcnt(12)
	v_pk_add_f32 v[116:117], v[116:117], v[194:195]
	v_pk_add_f32 v[114:115], v[114:115], v[192:193]
	v_pk_add_f32 v[100:101], v[100:101], v[198:199]
	v_pk_add_f32 v[98:99], v[98:99], v[196:197]
	v_pk_add_f32 v[68:69], v[68:69], v[202:203]
	v_pk_add_f32 v[66:67], v[66:67], v[200:201]
	v_pk_add_f32 v[48:49], v[48:49], v[206:207]
	v_pk_add_f32 v[46:47], v[46:47], v[204:205]
	global_load_dwordx4 v[192:195], v[238:239], off
	global_load_dwordx4 v[196:199], v[238:239], off offset:64
	global_load_dwordx4 v[200:203], v[238:239], off offset:512
	global_load_dwordx4 v[204:207], v[238:239], off offset:576
	s_waitcnt vmcnt(12)
	v_pk_add_f32 v[112:113], v[112:113], v[210:211]
	v_pk_add_f32 v[110:111], v[110:111], v[208:209]
	v_pk_add_f32 v[80:81], v[80:81], v[214:215]
	v_pk_add_f32 v[78:79], v[78:79], v[212:213]
	v_pk_add_f32 v[64:65], v[64:65], v[218:219]
	v_pk_add_f32 v[62:63], v[62:63], v[216:217]
	v_pk_add_f32 v[44:45], v[44:45], v[226:227]
	v_pk_add_f32 v[42:43], v[42:43], v[224:225]
	global_load_dwordx4 v[208:211], v[240:241], off
	global_load_dwordx4 v[212:215], v[240:241], off offset:64
	global_load_dwordx4 v[216:219], v[240:241], off offset:512
	global_load_dwordx4 v[224:227], v[240:241], off offset:576
	s_waitcnt vmcnt(12)
	v_pk_add_f32 v[108:109], v[108:109], v[134:135]
	v_pk_add_f32 v[106:107], v[106:107], v[132:133]
	v_pk_add_f32 v[76:77], v[76:77], v[140:141]
	v_pk_add_f32 v[74:75], v[74:75], v[138:139]
	v_pk_add_f32 v[56:57], v[56:57], v[144:145]
	v_pk_add_f32 v[54:55], v[54:55], v[142:143]
	v_pk_add_f32 v[36:37], v[36:37], v[162:163]
	v_pk_add_f32 v[34:35], v[34:35], v[160:161]
	s_waitcnt vmcnt(8)
	v_pk_add_f32 v[104:105], v[104:105], v[178:179]
	v_pk_add_f32 v[102:103], v[102:103], v[176:177]
	v_pk_add_f32 v[72:73], v[72:73], v[182:183]
	v_pk_add_f32 v[70:71], v[70:71], v[180:181]
	v_pk_add_f32 v[52:53], v[52:53], v[186:187]
	v_pk_add_f32 v[50:51], v[50:51], v[184:185]
	v_pk_add_f32 v[28:29], v[28:29], v[190:191]
	v_pk_add_f32 v[26:27], v[26:27], v[188:189]
	s_waitcnt vmcnt(4)
	v_pk_add_f32 v[40:41], v[40:41], v[194:195]
	v_pk_add_f32 v[38:39], v[38:39], v[192:193]
	v_pk_add_f32 v[32:33], v[32:33], v[198:199]
	v_pk_add_f32 v[30:31], v[30:31], v[196:197]
	v_pk_add_f32 v[24:25], v[24:25], v[202:203]
	v_pk_add_f32 v[22:23], v[22:23], v[200:201]
	v_pk_add_f32 v[20:21], v[20:21], v[206:207]
	v_pk_add_f32 v[18:19], v[18:19], v[204:205]
	s_waitcnt vmcnt(0)
	v_pk_add_f32 v[16:17], v[16:17], v[210:211]
	v_pk_add_f32 v[14:15], v[14:15], v[208:209]
	v_pk_add_f32 v[12:13], v[12:13], v[214:215]
	v_pk_add_f32 v[10:11], v[10:11], v[212:213]
	v_pk_add_f32 v[8:9], v[8:9], v[218:219]
	v_pk_add_f32 v[6:7], v[6:7], v[216:217]
	v_pk_add_f32 v[4:5], v[4:5], v[226:227]
	v_pk_add_f32 v[2:3], v[2:3], v[224:225]
	s_lshl_b32 s0, s1, 2
	s_add_i32 s4, s0, 0
	v_mul_f32_e32 v148, v89, v89
	v_mul_f32_e32 v155, v91, v91
	v_mul_f32_e32 v168, v93, v93
	v_fmac_f32_e32 v148, v88, v88
	v_mul_f32_e32 v169, v95, v95
	v_mul_f32_e32 v170, v97, v97
	v_fmac_f32_e32 v155, v90, v90
	v_fmac_f32_e32 v168, v92, v92
	v_fmac_f32_e32 v169, v94, v94
	v_fmac_f32_e32 v170, v96, v96
	v_mul_f32_e32 v133, v83, v83
	v_mul_f32_e32 v134, v85, v85
	v_mul_f32_e32 v135, v87, v87
	v_and_b32_e32 v131, 64, v158
	v_fmac_f32_e32 v133, v82, v82
	v_fmac_f32_e32 v134, v84, v84
	v_fmac_f32_e32 v135, v86, v86
	v_xor_b32_e32 v130, 16, v158
	v_add_u32_e32 v131, 64, v131
	v_add_f32_e32 v133, v133, v134
	v_add_f32_e32 v134, v135, v148
	v_cmp_lt_i32_e32 vcc, v130, v131
	v_add_f32_e32 v135, v155, v168
	v_add_f32_e32 v133, v133, v134
	v_cndmask_b32_e32 v130, v158, v130, vcc
	v_add_f32_e32 v148, v169, v170
	v_add_f32_e32 v133, v135, v133
	v_lshlrev_b32_e32 v130, 2, v130
	v_add_f32_e32 v133, v148, v133
	ds_bpermute_b32 v134, v130, v133
	v_xor_b32_e32 v135, 32, v158
	v_cmp_lt_i32_e32 vcc, v135, v131
	v_and_b32_e32 v132, 63, v136
	s_waitcnt lgkmcnt(0)
	v_add_f32_e32 v133, v133, v134
	v_cndmask_b32_e32 v131, v158, v135, vcc
	v_lshlrev_b32_e32 v131, 2, v131
	ds_bpermute_b32 v134, v131, v133
	v_cmp_gt_u32_e32 vcc, 16, v132
	s_nop 0
	s_and_saveexec_b64 s[0:1], vcc
	s_cbranch_execz .LBB0_808
	s_lshl_b32 s5, s40, 10
	s_add_i32 s5, s4, s5
	s_waitcnt lgkmcnt(0)
	v_add_f32_e32 v133, v133, v134
	v_lshl_add_u32 v134, v137, 4, s5
	ds_write_b32 v134, v133
